# v5b plus lagging half's restore barrier moved one store block before the end of its GEMM1 epilogue (leading half's first MFMA segment overlaps the lagging half's epilogue tail); peeled-iteration vmcnt
# speedup vs baseline: 1.0004x; 1.0004x over previous
; __device__ __forceinline__ unsigned cvt_pk_bf16(float lo, float hi) { unsigned r; asm volatile("v_cvt_pk_bf16_f32 %0, %1, %2" : "=v"(r) : "v"(lo), "v"(hi)); return r; }
; __device__ __forceinline__ f32x4 gelu4(f32x4 v) { f32x2 a = gelu_pk((f32x2){v[0], v[1]}), b = gelu_pk((f32x2){v[2], v[3]}); return (f32x4){a.x, a.y, b.x, b.y}; }
; __device__ __forceinline__ f32x4 sigm4(f32x4 v) { return (f32x4){sigmoid_f(v[0]), sigmoid_f(v[1]), sigmoid_f(v[2]), sigmoid_f(v[3])}; }
; __device__ __forceinline__ f32x4 silu4(f32x4 v) { return v * sigm4(v); }
; #define PG8_BAR __builtin_amdgcn_s_barrier()
; template <class Epi>
; __device__ __forceinline__ void gemm_phase(LAS unsigned char* lds, const Gemm g, const StaticOrder& S, const Epi& E) {
;     ...
;         if (wr == 1) PG8_BAR;
;     __device__ __forceinline__ void operator()(const f32x4 (&acc)[2][2][4][2], const pg8::Unit& u, int wr, int wc, int fr, int fq) const {
;     ...
;                         f32x4 v0 = acc[ai][bj][m][0], v1 = acc[ai][bj][m][1];
;                         if (act == 5) { v0 = sigm4(v0); v1 = sigm4(v1);
;                             if (bj == 0) { const f32x4 b0 = sigm4(acc[ai][1][m][0]), b1 = sigm4(acc[ai][1][m][1]);
; #pragma unroll
;                                 for (int e = 0; e < 4; ++e) { v0[e] *= __builtin_amdgcn_rcpf(fmaxf(b0[e], 1e-20f)); v1[e] *= __builtin_amdgcn_rcpf(fmaxf(b1[e], 1e-20f)); } } }
;                         else if (act == 1) { v0 = gelu4(v0); v1 = gelu4(v1); }
;                         else if (act == 2) { v0 = silu4(v0); v1 = silu4(v1); }
;                         else if (act == 3) { v0 = sigm4(v0); v1 = sigm4(v1); }
;                         else if (act == 4) { v0 = v0 * 0.08838834764831845f; v1 = v1 * 0.08838834764831845f; }
;                         u32x4 w; w.x = cvt_pk_bf16(v0[0], v0[1]); w.y = cvt_pk_bf16(v0[2], v0[3]); w.z = cvt_pk_bf16(v1[0], v1[1]); w.w = cvt_pk_bf16(v1[2], v1[3]);
;                         __builtin_nontemporal_store(w, (u32x4*)(rowp + (size_t)bj * bjs));
.LBB0_396:
	v_lshl_add_u64 v[150:151], v[150:151], 0, s[92:93]
	v_lshl_add_u64 v[148:149], v[150:151], 1, v[148:149]
	v_cvt_pk_bf16_f32 v150, v152, v153
	v_cvt_pk_bf16_f32 v151, v154, v155
	v_cvt_pk_bf16_f32 v152, v156, v157
	v_cvt_pk_bf16_f32 v153, v158, v159
	s_and_b64 vcc, exec, s[8:9]
	s_mov_b64 s[8:9], -1
	global_store_dwordx4 v[148:149], v[150:153], off nt
	s_and_b64 s[98:99], s[4:5], s[14:15]
	s_cbranch_scc0 .Lepi_rb_a
	s_barrier
.Lepi_rb_a:
	s_cbranch_vccnz .LBB0_408
	s_and_b64 vcc, exec, s[6:7]
	s_mov_b64 s[6:7], -1
	s_cbranch_vccnz .LBB0_405
	s_andn2_b64 vcc, exec, s[90:91]
	s_cbranch_vccnz .LBB0_402
	s_andn2_b64 vcc, exec, s[88:89]
	v_mov_b32_e32 v157, v3
	v_mov_b32_e32 v156, v2
	v_mov_b32_e32 v155, v1
	v_mov_b32_e32 v154, v0
	v_mov_b32_e32 v153, v11
	v_mov_b32_e32 v152, v10
	v_mov_b32_e32 v151, v9
	v_mov_b32_e32 v150, v8
	s_cbranch_vccnz .LBB0_401
	v_pk_mul_f32 v[152:153], v[10:11], s[26:27] op_sel_hi:[1,0]
	v_pk_mul_f32 v[150:151], v[8:9], s[26:27] op_sel_hi:[1,0]
	v_pk_mul_f32 v[156:157], v[2:3], s[26:27] op_sel_hi:[1,0]
	v_pk_mul_f32 v[154:155], v[0:1], s[26:27] op_sel_hi:[1,0]

; __device__ __forceinline__ unsigned cvt_pk_bf16(float lo, float hi) { unsigned r; asm volatile("v_cvt_pk_bf16_f32 %0, %1, %2" : "=v"(r) : "v"(lo), "v"(hi)); return r; }
; __device__ __forceinline__ f32x4 gelu4(f32x4 v) { f32x2 a = gelu_pk((f32x2){v[0], v[1]}), b = gelu_pk((f32x2){v[2], v[3]}); return (f32x4){a.x, a.y, b.x, b.y}; }
; __device__ __forceinline__ f32x4 silu4(f32x4 v) { return v * sigm4(v); }
; __device__ __forceinline__ f32x2 gelu_pk(f32x2 v) {
;     const f32x2 av = __builtin_elementwise_abs(v), d = av * 0.2316418882f + 1.0f;
;     f32x2 t; t.x = __builtin_amdgcn_rcpf(d.x); t.y = __builtin_amdgcn_rcpf(d.y);
;     f32x2 q = t * 0.5307027145f + (-0.7265760135f); q = q * t + 0.7107068705f; q = q * t + (-0.142248368f); q = q * t + 0.127414796f; q = q * t;
;     const f32x2 s = (v * v) * (-0.72134752044f);
;     f32x2 e; e.x = __builtin_amdgcn_exp2f(s.x); e.y = __builtin_amdgcn_exp2f(s.y);
;     const f32x2 m = v * (q * e), r = v - m;
;     f32x2 o; o.x = v.x < 0.f ? m.x : r.x; o.y = v.y < 0.f ? m.y : r.y; return o;
;     __device__ __forceinline__ void operator()(const f32x4 (&acc)[2][2][4][2], const pg8::Unit& u, int wr, int wc, int fr, int fq) const {
;     ...
;                 for (int m = 0; m < 4; ++m) {
;                     bf16_t* rowp = base + (size_t)(row0 + ai * 128 + m * 16) * 1024;
;                     const f32x4 v0 = gelu4(acc[ai][0][m][0]) * silu4(acc[ai][1][m][0]), v1 = gelu4(acc[ai][0][m][1]) * silu4(acc[ai][1][m][1]);
;                     u32x4 w; w.x = cvt_pk_bf16(v0[0], v0[1]); w.y = cvt_pk_bf16(v0[2], v0[3]); w.z = cvt_pk_bf16(v1[0], v1[1]); w.w = cvt_pk_bf16(v1[2], v1[3]);
;                     __builtin_nontemporal_store(w, (u32x4*)rowp);
.Lepi_nb_b:
	v_pk_mul_f32 v[118:119], v[108:109], v[108:109]
	v_and_b32_e32 v120, 0x7fffffff, v110
	v_and_b32_e32 v115, 0x7fffffff, v109
	v_and_b32_e32 v114, 0x7fffffff, v108
	v_pk_fma_f32 v[114:115], v[114:115], s[28:29], 1.0 op_sel_hi:[1,0,0]
	v_pk_mul_f32 v[118:119], v[118:119], s[74:75] op_sel_hi:[1,0]
	v_rcp_f32_e32 v114, v114
	v_rcp_f32_e32 v115, v115
	v_exp_f32_e32 v118, v118
	v_exp_f32_e32 v119, v119
	v_pk_fma_f32 v[120:121], v[120:121], s[28:29], 1.0 op_sel_hi:[1,0,0]
	v_pk_fma_f32 v[116:117], v[114:115], s[30:31], v[150:151] op_sel_hi:[1,0,0]
	v_rcp_f32_e32 v120, v120
	v_pk_fma_f32 v[116:117], v[114:115], v[116:117], s[36:37] op_sel_hi:[1,1,0]
	v_rcp_f32_e32 v121, v121
	v_pk_fma_f32 v[116:117], v[114:115], v[116:117], s[50:51] op_sel_hi:[1,1,0]
	v_or_b32_e32 v112, 16, v146
	v_pk_fma_f32 v[116:117], v[114:115], v[116:117], s[72:73] op_sel_hi:[1,1,0]
	v_ashrrev_i32_e32 v113, 31, v112
	v_pk_mul_f32 v[114:115], v[114:115], v[116:117]
	v_pk_mul_f32 v[116:117], v[110:111], v[110:111]
	v_pk_mul_f32 v[114:115], v[118:119], v[114:115]
	v_pk_mul_f32 v[116:117], v[116:117], s[74:75] op_sel_hi:[1,0]
	v_pk_mul_f32 v[118:119], v[108:109], v[114:115]
	v_pk_fma_f32 v[114:115], v[108:109], v[114:115], v[108:109] neg_lo:[1,0,0] neg_hi:[1,0,0]
	v_exp_f32_e32 v116, v116
	v_cndmask_b32_e32 v108, v114, v118, vcc
	v_cmp_gt_f32_e32 vcc, 0, v109
	v_exp_f32_e32 v117, v117
	v_lshlrev_b64 v[112:113], 11, v[112:113]
	v_cndmask_b32_e32 v109, v115, v119, vcc
	v_pk_fma_f32 v[114:115], v[120:121], s[30:31], v[150:151] op_sel_hi:[1,0,0]
	v_cmp_gt_f32_e32 vcc, 0, v110
	v_pk_fma_f32 v[114:115], v[120:121], v[114:115], s[36:37] op_sel_hi:[1,1,0]
	v_lshl_add_u64 v[112:113], v[152:153], 0, v[112:113]
	v_pk_fma_f32 v[114:115], v[120:121], v[114:115], s[50:51] op_sel_hi:[1,1,0]
	s_mov_b32 s6, 0x40000
	v_pk_fma_f32 v[114:115], v[120:121], v[114:115], s[72:73] op_sel_hi:[1,1,0]
	s_nop 0
	v_pk_mul_f32 v[114:115], v[120:121], v[114:115]
	s_nop 0
	v_pk_mul_f32 v[114:115], v[116:117], v[114:115]
	s_nop 0
	v_pk_mul_f32 v[116:117], v[110:111], v[114:115]
	v_pk_fma_f32 v[114:115], v[110:111], v[114:115], v[110:111] neg_lo:[1,0,0] neg_hi:[1,0,0]
	s_nop 0
	v_cndmask_b32_e32 v110, v114, v116, vcc
	v_mul_f32_e32 v116, 0xbfb8aa3b, v105
	v_mul_f32_e32 v114, 0xbfb8aa3b, v104
	v_exp_f32_e32 v116, v116
	v_exp_f32_e32 v114, v114
	v_cmp_gt_f32_e32 vcc, 0, v111
	v_add_f32_e32 v114, 1.0, v114
	s_nop 0
	v_cndmask_b32_e32 v111, v115, v117, vcc
	v_add_f32_e32 v115, 1.0, v116
	v_mul_f32_e32 v116, 0xbfb8aa3b, v106
	v_mul_f32_e32 v117, 0xbfb8aa3b, v107
	v_exp_f32_e32 v116, v116
	v_exp_f32_e32 v117, v117
	v_rcp_f32_e32 v114, v114
	v_rcp_f32_e32 v115, v115
	v_add_f32_e32 v116, 1.0, v116
	v_add_f32_e32 v117, 1.0, v117
	v_rcp_f32_e32 v116, v116
	v_rcp_f32_e32 v117, v117
	v_pk_mul_f32 v[104:105], v[104:105], v[114:115]
	v_and_b32_e32 v115, 0x7fffffff, v101
	v_and_b32_e32 v114, 0x7fffffff, v100
	v_pk_fma_f32 v[114:115], v[114:115], s[28:29], 1.0 op_sel_hi:[1,0,0]
	v_pk_mul_f32 v[106:107], v[106:107], v[116:117]
	v_rcp_f32_e32 v114, v114
	v_rcp_f32_e32 v115, v115
	v_pk_mul_f32 v[106:107], v[110:111], v[106:107]
	v_pk_mul_f32 v[110:111], v[100:101], v[100:101]
	v_pk_mul_f32 v[104:105], v[108:109], v[104:105]
	v_pk_fma_f32 v[108:109], v[114:115], s[30:31], v[150:151] op_sel_hi:[1,0,0]
	v_pk_mul_f32 v[110:111], v[110:111], s[74:75] op_sel_hi:[1,0]
	v_pk_fma_f32 v[108:109], v[114:115], v[108:109], s[36:37] op_sel_hi:[1,1,0]
	v_exp_f32_e32 v110, v110
	v_exp_f32_e32 v111, v111
	v_pk_fma_f32 v[108:109], v[114:115], v[108:109], s[50:51] op_sel_hi:[1,1,0]
	v_and_b32_e32 v117, 0x7fffffff, v103
	v_and_b32_e32 v116, 0x7fffffff, v102
	v_pk_fma_f32 v[108:109], v[114:115], v[108:109], s[72:73] op_sel_hi:[1,1,0]
	v_pk_fma_f32 v[116:117], v[116:117], s[28:29], 1.0 op_sel_hi:[1,0,0]
	v_pk_mul_f32 v[108:109], v[114:115], v[108:109]
	v_rcp_f32_e32 v116, v116
	v_rcp_f32_e32 v117, v117
	v_pk_mul_f32 v[108:109], v[110:111], v[108:109]
	v_cmp_gt_f32_e32 vcc, 0, v100
	v_pk_mul_f32 v[110:111], v[100:101], v[108:109]
	v_pk_fma_f32 v[108:109], v[100:101], v[108:109], v[100:101] neg_lo:[1,0,0] neg_hi:[1,0,0]
	v_pk_mul_f32 v[114:115], v[102:103], v[102:103]
	v_cndmask_b32_e32 v100, v108, v110, vcc
	v_cmp_gt_f32_e32 vcc, 0, v101
	s_nop 1
	v_cndmask_b32_e32 v101, v109, v111, vcc
	v_pk_fma_f32 v[108:109], v[116:117], s[30:31], v[150:151] op_sel_hi:[1,0,0]
	v_pk_mul_f32 v[110:111], v[114:115], s[74:75] op_sel_hi:[1,0]
	v_pk_fma_f32 v[108:109], v[116:117], v[108:109], s[36:37] op_sel_hi:[1,1,0]
	v_exp_f32_e32 v110, v110
	v_exp_f32_e32 v111, v111
	v_pk_fma_f32 v[108:109], v[116:117], v[108:109], s[50:51] op_sel_hi:[1,1,0]
	v_mul_f32_e32 v114, 0xbfb8aa3b, v96
	v_pk_fma_f32 v[108:109], v[116:117], v[108:109], s[72:73] op_sel_hi:[1,1,0]
	v_exp_f32_e32 v114, v114
	v_mul_f32_e32 v115, 0xbfb8aa3b, v97
	v_pk_mul_f32 v[108:109], v[116:117], v[108:109]
	v_exp_f32_e32 v115, v115
	v_pk_mul_f32 v[108:109], v[110:111], v[108:109]
	v_cmp_gt_f32_e32 vcc, 0, v102
	v_pk_mul_f32 v[110:111], v[102:103], v[108:109]
	v_pk_fma_f32 v[108:109], v[102:103], v[108:109], v[102:103] neg_lo:[1,0,0] neg_hi:[1,0,0]
	s_nop 0
	v_cndmask_b32_e32 v102, v108, v110, vcc
	v_add_f32_e32 v108, 1.0, v114
	v_mul_f32_e32 v110, 0xbfb8aa3b, v98
	v_rcp_f32_e32 v114, v108
	v_add_f32_e32 v108, 1.0, v115
	v_exp_f32_e32 v110, v110
	v_mul_f32_e32 v115, 0xbfb8aa3b, v99
	v_exp_f32_e32 v117, v115
	v_rcp_f32_e32 v115, v108
	v_add_f32_e32 v108, 1.0, v110
	v_rcp_f32_e32 v116, v108
	v_add_f32_e32 v108, 1.0, v117
	v_rcp_f32_e32 v117, v108
	v_cmp_gt_f32_e32 vcc, 0, v103
	v_pk_mul_f32 v[96:97], v[96:97], v[114:115]
	v_pk_mul_f32 v[98:99], v[98:99], v[116:117]
	v_cndmask_b32_e32 v103, v109, v111, vcc
; __device__ __forceinline__ unsigned cvt_pk_bf16(float lo, float hi) { unsigned r; asm volatile("v_cvt_pk_bf16_f32 %0, %1, %2" : "=v"(r) : "v"(lo), "v"(hi)); return r; }
; __device__ __forceinline__ f32x4 gelu4(f32x4 v) { f32x2 a = gelu_pk((f32x2){v[0], v[1]}), b = gelu_pk((f32x2){v[2], v[3]}); return (f32x4){a.x, a.y, b.x, b.y}; }
; __device__ __forceinline__ f32x4 silu4(f32x4 v) { return v * sigm4(v); }
;     __device__ __forceinline__ void operator()(const f32x4 (&acc)[2][2][4][2], const pg8::Unit& u, int wr, int wc, int fr, int fq) const {
;     ...
;                 for (int m = 0; m < 4; ++m) {
;                     bf16_t* rowp = base + (size_t)(row0 + ai * 128 + m * 16) * 1024;
;                     const f32x4 v0 = gelu4(acc[ai][0][m][0]) * silu4(acc[ai][1][m][0]), v1 = gelu4(acc[ai][0][m][1]) * silu4(acc[ai][1][m][1]);
;                     u32x4 w; w.x = cvt_pk_bf16(v0[0], v0[1]); w.y = cvt_pk_bf16(v0[2], v0[3]); w.z = cvt_pk_bf16(v1[0], v1[1]); w.w = cvt_pk_bf16(v1[2], v1[3]);
;                     __builtin_nontemporal_store(w, (u32x4*)rowp);
	v_pk_mul_f32 v[102:103], v[102:103], v[98:99]
	v_pk_mul_f32 v[98:99], v[100:101], v[96:97]
	v_cvt_pk_bf16_f32 v96, v104, v105
	v_cvt_pk_bf16_f32 v97, v106, v107
	v_and_b32_e32 v105, 0x7fffffff, v95
	v_cvt_pk_bf16_f32 v98, v98, v99
	v_cvt_pk_bf16_f32 v99, v102, v103
	global_store_dwordx4 v[112:113], v[96:99], off nt
	v_pk_mul_f32 v[102:103], v[92:93], v[92:93]
	v_and_b32_e32 v104, 0x7fffffff, v94
	v_and_b32_e32 v99, 0x7fffffff, v93
	v_and_b32_e32 v98, 0x7fffffff, v92
	v_pk_fma_f32 v[98:99], v[98:99], s[28:29], 1.0 op_sel_hi:[1,0,0]
	v_pk_mul_f32 v[102:103], v[102:103], s[74:75] op_sel_hi:[1,0]
	v_rcp_f32_e32 v98, v98
	v_rcp_f32_e32 v99, v99
	v_exp_f32_e32 v102, v102
	v_exp_f32_e32 v103, v103
	v_pk_fma_f32 v[104:105], v[104:105], s[28:29], 1.0 op_sel_hi:[1,0,0]
	v_pk_fma_f32 v[100:101], v[98:99], s[30:31], v[150:151] op_sel_hi:[1,0,0]
	v_rcp_f32_e32 v104, v104
	v_pk_fma_f32 v[100:101], v[98:99], v[100:101], s[36:37] op_sel_hi:[1,1,0]
	v_rcp_f32_e32 v105, v105
	v_pk_fma_f32 v[100:101], v[98:99], v[100:101], s[50:51] op_sel_hi:[1,1,0]
	v_cmp_gt_f32_e32 vcc, 0, v92
	v_pk_fma_f32 v[100:101], v[98:99], v[100:101], s[72:73] op_sel_hi:[1,1,0]
	v_or_b32_e32 v96, 32, v146
	v_pk_mul_f32 v[98:99], v[98:99], v[100:101]
	v_pk_mul_f32 v[100:101], v[94:95], v[94:95]
	v_pk_mul_f32 v[98:99], v[102:103], v[98:99]
	v_pk_mul_f32 v[100:101], v[100:101], s[74:75] op_sel_hi:[1,0]
	v_pk_mul_f32 v[102:103], v[92:93], v[98:99]
	v_pk_fma_f32 v[98:99], v[92:93], v[98:99], v[92:93] neg_lo:[1,0,0] neg_hi:[1,0,0]
	v_exp_f32_e32 v100, v100
	v_cndmask_b32_e32 v92, v98, v102, vcc
	v_cmp_gt_f32_e32 vcc, 0, v93
	v_exp_f32_e32 v101, v101
	v_ashrrev_i32_e32 v97, 31, v96
	v_cndmask_b32_e32 v93, v99, v103, vcc
	v_pk_fma_f32 v[98:99], v[104:105], s[30:31], v[150:151] op_sel_hi:[1,0,0]
	v_cmp_gt_f32_e32 vcc, 0, v94
	v_pk_fma_f32 v[98:99], v[104:105], v[98:99], s[36:37] op_sel_hi:[1,1,0]
	v_lshlrev_b64 v[96:97], 11, v[96:97]
	v_pk_fma_f32 v[98:99], v[104:105], v[98:99], s[50:51] op_sel_hi:[1,1,0]
	v_lshl_add_u64 v[96:97], v[152:153], 0, v[96:97]
	v_pk_fma_f32 v[98:99], v[104:105], v[98:99], s[72:73] op_sel_hi:[1,1,0]
	s_nop 0
	v_pk_mul_f32 v[98:99], v[104:105], v[98:99]
	s_nop 0
	v_pk_mul_f32 v[98:99], v[100:101], v[98:99]
	s_nop 0
	v_pk_mul_f32 v[100:101], v[94:95], v[98:99]
	v_pk_fma_f32 v[98:99], v[94:95], v[98:99], v[94:95] neg_lo:[1,0,0] neg_hi:[1,0,0]
	s_nop 0
	v_cndmask_b32_e32 v94, v98, v100, vcc
	v_mul_f32_e32 v100, 0xbfb8aa3b, v89
	v_mul_f32_e32 v98, 0xbfb8aa3b, v88
	v_exp_f32_e32 v100, v100
	v_exp_f32_e32 v98, v98
	v_cmp_gt_f32_e32 vcc, 0, v95
	v_add_f32_e32 v98, 1.0, v98
	s_nop 0
	v_cndmask_b32_e32 v95, v99, v101, vcc
	v_add_f32_e32 v99, 1.0, v100
	v_mul_f32_e32 v100, 0xbfb8aa3b, v90
	v_mul_f32_e32 v101, 0xbfb8aa3b, v91
	v_exp_f32_e32 v100, v100
	v_exp_f32_e32 v101, v101
	v_rcp_f32_e32 v98, v98
	v_rcp_f32_e32 v99, v99
	v_add_f32_e32 v100, 1.0, v100
	v_add_f32_e32 v101, 1.0, v101
	v_rcp_f32_e32 v100, v100
	v_rcp_f32_e32 v101, v101
	v_pk_mul_f32 v[88:89], v[88:89], v[98:99]
	v_and_b32_e32 v99, 0x7fffffff, v85
	v_and_b32_e32 v98, 0x7fffffff, v84
	v_pk_fma_f32 v[98:99], v[98:99], s[28:29], 1.0 op_sel_hi:[1,0,0]
	v_pk_mul_f32 v[90:91], v[90:91], v[100:101]
	v_rcp_f32_e32 v98, v98
	v_rcp_f32_e32 v99, v99
	v_pk_mul_f32 v[90:91], v[94:95], v[90:91]
	v_pk_mul_f32 v[94:95], v[84:85], v[84:85]
	v_pk_mul_f32 v[88:89], v[92:93], v[88:89]
	v_pk_fma_f32 v[92:93], v[98:99], s[30:31], v[150:151] op_sel_hi:[1,0,0]
	v_pk_mul_f32 v[94:95], v[94:95], s[74:75] op_sel_hi:[1,0]
	v_pk_fma_f32 v[92:93], v[98:99], v[92:93], s[36:37] op_sel_hi:[1,1,0]
	v_exp_f32_e32 v94, v94
	v_exp_f32_e32 v95, v95
	v_pk_fma_f32 v[92:93], v[98:99], v[92:93], s[50:51] op_sel_hi:[1,1,0]
	v_and_b32_e32 v101, 0x7fffffff, v87
	v_and_b32_e32 v100, 0x7fffffff, v86
	v_pk_fma_f32 v[92:93], v[98:99], v[92:93], s[72:73] op_sel_hi:[1,1,0]
	v_pk_fma_f32 v[100:101], v[100:101], s[28:29], 1.0 op_sel_hi:[1,0,0]
	v_pk_mul_f32 v[92:93], v[98:99], v[92:93]
	v_rcp_f32_e32 v100, v100
	v_rcp_f32_e32 v101, v101
	v_pk_mul_f32 v[92:93], v[94:95], v[92:93]
	v_cmp_gt_f32_e32 vcc, 0, v84
	v_pk_mul_f32 v[94:95], v[84:85], v[92:93]
	v_pk_fma_f32 v[92:93], v[84:85], v[92:93], v[84:85] neg_lo:[1,0,0] neg_hi:[1,0,0]
	v_pk_mul_f32 v[98:99], v[86:87], v[86:87]
	v_cndmask_b32_e32 v84, v92, v94, vcc
	v_cmp_gt_f32_e32 vcc, 0, v85
	s_nop 1
	v_cndmask_b32_e32 v85, v93, v95, vcc
	v_pk_fma_f32 v[92:93], v[100:101], s[30:31], v[150:151] op_sel_hi:[1,0,0]
	v_pk_mul_f32 v[94:95], v[98:99], s[74:75] op_sel_hi:[1,0]
	v_pk_fma_f32 v[92:93], v[100:101], v[92:93], s[36:37] op_sel_hi:[1,1,0]
	v_exp_f32_e32 v94, v94
	v_exp_f32_e32 v95, v95
	v_pk_fma_f32 v[92:93], v[100:101], v[92:93], s[50:51] op_sel_hi:[1,1,0]
	v_mul_f32_e32 v98, 0xbfb8aa3b, v80
	v_pk_fma_f32 v[92:93], v[100:101], v[92:93], s[72:73] op_sel_hi:[1,1,0]
	v_exp_f32_e32 v98, v98
	v_mul_f32_e32 v99, 0xbfb8aa3b, v81
	v_pk_mul_f32 v[92:93], v[100:101], v[92:93]
	v_exp_f32_e32 v99, v99
	v_pk_mul_f32 v[92:93], v[94:95], v[92:93]
	v_cmp_gt_f32_e32 vcc, 0, v86
	v_pk_mul_f32 v[94:95], v[86:87], v[92:93]
	v_pk_fma_f32 v[92:93], v[86:87], v[92:93], v[86:87] neg_lo:[1,0,0] neg_hi:[1,0,0]
	s_nop 0
	v_cndmask_b32_e32 v86, v92, v94, vcc
	v_add_f32_e32 v92, 1.0, v98
	v_mul_f32_e32 v94, 0xbfb8aa3b, v82
	v_rcp_f32_e32 v98, v92
	v_add_f32_e32 v92, 1.0, v99
	v_exp_f32_e32 v94, v94
	v_mul_f32_e32 v99, 0xbfb8aa3b, v83
	v_exp_f32_e32 v101, v99
	v_rcp_f32_e32 v99, v92
	v_add_f32_e32 v92, 1.0, v94
	v_rcp_f32_e32 v100, v92
	v_add_f32_e32 v92, 1.0, v101
	v_rcp_f32_e32 v101, v92
	v_cmp_gt_f32_e32 vcc, 0, v87
	v_pk_mul_f32 v[80:81], v[80:81], v[98:99]
	v_pk_mul_f32 v[82:83], v[82:83], v[100:101]
	v_cndmask_b32_e32 v87, v93, v95, vcc
; __device__ __forceinline__ unsigned cvt_pk_bf16(float lo, float hi) { unsigned r; asm volatile("v_cvt_pk_bf16_f32 %0, %1, %2" : "=v"(r) : "v"(lo), "v"(hi)); return r; }
; __device__ __forceinline__ f32x4 gelu4(f32x4 v) { f32x2 a = gelu_pk((f32x2){v[0], v[1]}), b = gelu_pk((f32x2){v[2], v[3]}); return (f32x4){a.x, a.y, b.x, b.y}; }
; __device__ __forceinline__ f32x4 silu4(f32x4 v) { return v * sigm4(v); }
;     __device__ __forceinline__ void operator()(const f32x4 (&acc)[2][2][4][2], const pg8::Unit& u, int wr, int wc, int fr, int fq) const {
;     ...
;                 for (int m = 0; m < 4; ++m) {
;                     bf16_t* rowp = base + (size_t)(row0 + ai * 128 + m * 16) * 1024;
;                     const f32x4 v0 = gelu4(acc[ai][0][m][0]) * silu4(acc[ai][1][m][0]), v1 = gelu4(acc[ai][0][m][1]) * silu4(acc[ai][1][m][1]);
;                     u32x4 w; w.x = cvt_pk_bf16(v0[0], v0[1]); w.y = cvt_pk_bf16(v0[2], v0[3]); w.z = cvt_pk_bf16(v1[0], v1[1]); w.w = cvt_pk_bf16(v1[2], v1[3]);
;                     __builtin_nontemporal_store(w, (u32x4*)rowp);
	v_pk_mul_f32 v[86:87], v[86:87], v[82:83]
	v_pk_mul_f32 v[82:83], v[84:85], v[80:81]
	v_cvt_pk_bf16_f32 v80, v88, v89
	v_cvt_pk_bf16_f32 v81, v90, v91
	v_and_b32_e32 v89, 0x7fffffff, v79
	v_cvt_pk_bf16_f32 v82, v82, v83
	v_cvt_pk_bf16_f32 v83, v86, v87
	global_store_dwordx4 v[96:97], v[80:83], off nt
	v_pk_mul_f32 v[86:87], v[76:77], v[76:77]
	v_and_b32_e32 v88, 0x7fffffff, v78
	v_and_b32_e32 v83, 0x7fffffff, v77
	v_and_b32_e32 v82, 0x7fffffff, v76
	v_pk_fma_f32 v[82:83], v[82:83], s[28:29], 1.0 op_sel_hi:[1,0,0]
	v_pk_mul_f32 v[86:87], v[86:87], s[74:75] op_sel_hi:[1,0]
	v_rcp_f32_e32 v82, v82
	v_rcp_f32_e32 v83, v83
	v_exp_f32_e32 v86, v86
	v_exp_f32_e32 v87, v87
	v_pk_fma_f32 v[88:89], v[88:89], s[28:29], 1.0 op_sel_hi:[1,0,0]
	v_pk_fma_f32 v[84:85], v[82:83], s[30:31], v[150:151] op_sel_hi:[1,0,0]
	v_rcp_f32_e32 v88, v88
	v_pk_fma_f32 v[84:85], v[82:83], v[84:85], s[36:37] op_sel_hi:[1,1,0]
	v_rcp_f32_e32 v89, v89
	v_pk_fma_f32 v[84:85], v[82:83], v[84:85], s[50:51] op_sel_hi:[1,1,0]
	v_cmp_gt_f32_e32 vcc, 0, v76
	v_pk_fma_f32 v[84:85], v[82:83], v[84:85], s[72:73] op_sel_hi:[1,1,0]
	v_or_b32_e32 v80, 48, v146
	v_pk_mul_f32 v[82:83], v[82:83], v[84:85]
	v_pk_mul_f32 v[84:85], v[78:79], v[78:79]
	v_pk_mul_f32 v[82:83], v[86:87], v[82:83]
	v_pk_mul_f32 v[84:85], v[84:85], s[74:75] op_sel_hi:[1,0]
	v_pk_mul_f32 v[86:87], v[76:77], v[82:83]
	v_pk_fma_f32 v[82:83], v[76:77], v[82:83], v[76:77] neg_lo:[1,0,0] neg_hi:[1,0,0]
	v_exp_f32_e32 v84, v84
	v_cndmask_b32_e32 v76, v82, v86, vcc
	v_cmp_gt_f32_e32 vcc, 0, v77
	v_exp_f32_e32 v85, v85
	v_ashrrev_i32_e32 v81, 31, v80
	v_cndmask_b32_e32 v77, v83, v87, vcc
	v_pk_fma_f32 v[82:83], v[88:89], s[30:31], v[150:151] op_sel_hi:[1,0,0]
	v_cmp_gt_f32_e32 vcc, 0, v78
	v_pk_fma_f32 v[82:83], v[88:89], v[82:83], s[36:37] op_sel_hi:[1,1,0]
	v_lshlrev_b64 v[80:81], 11, v[80:81]
	v_pk_fma_f32 v[82:83], v[88:89], v[82:83], s[50:51] op_sel_hi:[1,1,0]
	v_lshl_add_u64 v[80:81], v[152:153], 0, v[80:81]
	v_pk_fma_f32 v[82:83], v[88:89], v[82:83], s[72:73] op_sel_hi:[1,1,0]
	s_nop 0
	v_pk_mul_f32 v[82:83], v[88:89], v[82:83]
	s_nop 0
	v_pk_mul_f32 v[82:83], v[84:85], v[82:83]
	s_nop 0
	v_pk_mul_f32 v[84:85], v[78:79], v[82:83]
	v_pk_fma_f32 v[82:83], v[78:79], v[82:83], v[78:79] neg_lo:[1,0,0] neg_hi:[1,0,0]
	s_nop 0
	v_cndmask_b32_e32 v78, v82, v84, vcc
	v_mul_f32_e32 v84, 0xbfb8aa3b, v73
	v_mul_f32_e32 v82, 0xbfb8aa3b, v72
	v_exp_f32_e32 v84, v84
	v_exp_f32_e32 v82, v82
	v_cmp_gt_f32_e32 vcc, 0, v79
	v_add_f32_e32 v82, 1.0, v82
	s_nop 0
	v_cndmask_b32_e32 v79, v83, v85, vcc
	v_add_f32_e32 v83, 1.0, v84
	v_mul_f32_e32 v84, 0xbfb8aa3b, v74
	v_mul_f32_e32 v85, 0xbfb8aa3b, v75
	v_exp_f32_e32 v84, v84
	v_exp_f32_e32 v85, v85
	v_rcp_f32_e32 v82, v82
	v_rcp_f32_e32 v83, v83
	v_add_f32_e32 v84, 1.0, v84
	v_add_f32_e32 v85, 1.0, v85
	v_rcp_f32_e32 v84, v84
	v_rcp_f32_e32 v85, v85
	v_pk_mul_f32 v[72:73], v[72:73], v[82:83]
	v_and_b32_e32 v83, 0x7fffffff, v69
	v_and_b32_e32 v82, 0x7fffffff, v68
	v_pk_fma_f32 v[82:83], v[82:83], s[28:29], 1.0 op_sel_hi:[1,0,0]
	v_pk_mul_f32 v[74:75], v[74:75], v[84:85]
	v_rcp_f32_e32 v82, v82
	v_rcp_f32_e32 v83, v83
	v_pk_mul_f32 v[74:75], v[78:79], v[74:75]
	v_pk_mul_f32 v[78:79], v[68:69], v[68:69]
	v_pk_mul_f32 v[72:73], v[76:77], v[72:73]
	v_pk_fma_f32 v[76:77], v[82:83], s[30:31], v[150:151] op_sel_hi:[1,0,0]
	v_pk_mul_f32 v[78:79], v[78:79], s[74:75] op_sel_hi:[1,0]
	v_pk_fma_f32 v[76:77], v[82:83], v[76:77], s[36:37] op_sel_hi:[1,1,0]
	v_exp_f32_e32 v78, v78
	v_exp_f32_e32 v79, v79
	v_pk_fma_f32 v[76:77], v[82:83], v[76:77], s[50:51] op_sel_hi:[1,1,0]
	v_and_b32_e32 v85, 0x7fffffff, v71
	v_and_b32_e32 v84, 0x7fffffff, v70
	v_pk_fma_f32 v[76:77], v[82:83], v[76:77], s[72:73] op_sel_hi:[1,1,0]
	v_pk_fma_f32 v[84:85], v[84:85], s[28:29], 1.0 op_sel_hi:[1,0,0]
	v_pk_mul_f32 v[76:77], v[82:83], v[76:77]
	v_rcp_f32_e32 v84, v84
	v_rcp_f32_e32 v85, v85
	v_pk_mul_f32 v[76:77], v[78:79], v[76:77]
	v_cmp_gt_f32_e32 vcc, 0, v68
	v_pk_mul_f32 v[78:79], v[68:69], v[76:77]
	v_pk_fma_f32 v[76:77], v[68:69], v[76:77], v[68:69] neg_lo:[1,0,0] neg_hi:[1,0,0]
	v_pk_mul_f32 v[82:83], v[70:71], v[70:71]
	v_cndmask_b32_e32 v68, v76, v78, vcc
	v_cmp_gt_f32_e32 vcc, 0, v69
	s_nop 1
	v_cndmask_b32_e32 v69, v77, v79, vcc
	v_pk_fma_f32 v[76:77], v[84:85], s[30:31], v[150:151] op_sel_hi:[1,0,0]
	v_pk_mul_f32 v[78:79], v[82:83], s[74:75] op_sel_hi:[1,0]
	v_pk_fma_f32 v[76:77], v[84:85], v[76:77], s[36:37] op_sel_hi:[1,1,0]
	v_exp_f32_e32 v78, v78
	v_exp_f32_e32 v79, v79
	v_pk_fma_f32 v[76:77], v[84:85], v[76:77], s[50:51] op_sel_hi:[1,1,0]
	v_mul_f32_e32 v82, 0xbfb8aa3b, v64
	v_pk_fma_f32 v[76:77], v[84:85], v[76:77], s[72:73] op_sel_hi:[1,1,0]
	v_exp_f32_e32 v82, v82
	v_mul_f32_e32 v83, 0xbfb8aa3b, v65
	v_pk_mul_f32 v[76:77], v[84:85], v[76:77]
	v_exp_f32_e32 v83, v83
	v_pk_mul_f32 v[76:77], v[78:79], v[76:77]
	v_cmp_gt_f32_e32 vcc, 0, v70
	v_pk_mul_f32 v[78:79], v[70:71], v[76:77]
	v_pk_fma_f32 v[76:77], v[70:71], v[76:77], v[70:71] neg_lo:[1,0,0] neg_hi:[1,0,0]
	s_nop 0
	v_cndmask_b32_e32 v70, v76, v78, vcc
	v_add_f32_e32 v76, 1.0, v82
	v_mul_f32_e32 v78, 0xbfb8aa3b, v66
	v_rcp_f32_e32 v82, v76
	v_add_f32_e32 v76, 1.0, v83
	v_exp_f32_e32 v78, v78
	v_mul_f32_e32 v83, 0xbfb8aa3b, v67
	v_exp_f32_e32 v85, v83
	v_rcp_f32_e32 v83, v76
	v_add_f32_e32 v76, 1.0, v78
	v_rcp_f32_e32 v84, v76
	v_add_f32_e32 v76, 1.0, v85
	v_rcp_f32_e32 v85, v76
	v_cmp_gt_f32_e32 vcc, 0, v71
	v_pk_mul_f32 v[64:65], v[64:65], v[82:83]
	v_pk_mul_f32 v[66:67], v[66:67], v[84:85]
	v_cndmask_b32_e32 v71, v77, v79, vcc
	v_pk_mul_f32 v[70:71], v[70:71], v[66:67]
	v_pk_mul_f32 v[66:67], v[68:69], v[64:65]
	v_and_b32_e32 v69, 0x7fffffff, v61
; __device__ __forceinline__ unsigned cvt_pk_bf16(float lo, float hi) { unsigned r; asm volatile("v_cvt_pk_bf16_f32 %0, %1, %2" : "=v"(r) : "v"(lo), "v"(hi)); return r; }
; __device__ __forceinline__ f32x4 gelu4(f32x4 v) { f32x2 a = gelu_pk((f32x2){v[0], v[1]}), b = gelu_pk((f32x2){v[2], v[3]}); return (f32x4){a.x, a.y, b.x, b.y}; }
; __device__ __forceinline__ f32x4 silu4(f32x4 v) { return v * sigm4(v); }
;     __device__ __forceinline__ void operator()(const f32x4 (&acc)[2][2][4][2], const pg8::Unit& u, int wr, int wc, int fr, int fq) const {
;     ...
;                 for (int m = 0; m < 4; ++m) {
;                     bf16_t* rowp = base + (size_t)(row0 + ai * 128 + m * 16) * 1024;
;                     const f32x4 v0 = gelu4(acc[ai][0][m][0]) * silu4(acc[ai][1][m][0]), v1 = gelu4(acc[ai][0][m][1]) * silu4(acc[ai][1][m][1]);
;                     u32x4 w; w.x = cvt_pk_bf16(v0[0], v0[1]); w.y = cvt_pk_bf16(v0[2], v0[3]); w.z = cvt_pk_bf16(v1[0], v1[1]); w.w = cvt_pk_bf16(v1[2], v1[3]);
;                     __builtin_nontemporal_store(w, (u32x4*)rowp);
	v_and_b32_e32 v68, 0x7fffffff, v60
	v_pk_fma_f32 v[68:69], v[68:69], s[28:29], 1.0 op_sel_hi:[1,0,0]
	v_cvt_pk_bf16_f32 v64, v72, v73
	v_cvt_pk_bf16_f32 v65, v74, v75
	v_cvt_pk_bf16_f32 v66, v66, v67
	v_cvt_pk_bf16_f32 v67, v70, v71
	global_store_dwordx4 v[80:81], v[64:67], off nt
	v_rcp_f32_e32 v68, v68
	v_rcp_f32_e32 v69, v69
	v_pk_mul_f32 v[66:67], v[60:61], v[60:61]
	v_and_b32_e32 v71, 0x7fffffff, v63
	v_pk_mul_f32 v[66:67], v[66:67], s[74:75] op_sel_hi:[1,0]
	v_pk_fma_f32 v[64:65], v[68:69], s[30:31], v[150:151] op_sel_hi:[1,0,0]
	v_exp_f32_e32 v66, v66
	v_pk_fma_f32 v[64:65], v[68:69], v[64:65], s[36:37] op_sel_hi:[1,1,0]
	v_exp_f32_e32 v67, v67
	v_pk_fma_f32 v[64:65], v[68:69], v[64:65], s[50:51] op_sel_hi:[1,1,0]
	v_and_b32_e32 v70, 0x7fffffff, v62
	v_pk_fma_f32 v[64:65], v[68:69], v[64:65], s[72:73] op_sel_hi:[1,1,0]
	v_pk_fma_f32 v[70:71], v[70:71], s[28:29], 1.0 op_sel_hi:[1,0,0]
	v_pk_mul_f32 v[64:65], v[68:69], v[64:65]
	v_rcp_f32_e32 v70, v70
	v_rcp_f32_e32 v71, v71
	v_pk_mul_f32 v[64:65], v[66:67], v[64:65]
	v_cmp_gt_f32_e32 vcc, 0, v60
	v_pk_mul_f32 v[66:67], v[60:61], v[64:65]
	v_pk_fma_f32 v[64:65], v[60:61], v[64:65], v[60:61] neg_lo:[1,0,0] neg_hi:[1,0,0]
	v_pk_mul_f32 v[68:69], v[62:63], v[62:63]
	v_cndmask_b32_e32 v60, v64, v66, vcc
	v_cmp_gt_f32_e32 vcc, 0, v61
	s_nop 1
	v_cndmask_b32_e32 v61, v65, v67, vcc
	v_pk_fma_f32 v[64:65], v[70:71], s[30:31], v[150:151] op_sel_hi:[1,0,0]
	v_pk_mul_f32 v[66:67], v[68:69], s[74:75] op_sel_hi:[1,0]
	v_pk_fma_f32 v[64:65], v[70:71], v[64:65], s[36:37] op_sel_hi:[1,1,0]
	v_exp_f32_e32 v66, v66
	v_exp_f32_e32 v67, v67
	v_pk_fma_f32 v[64:65], v[70:71], v[64:65], s[50:51] op_sel_hi:[1,1,0]
	v_cmp_gt_f32_e32 vcc, 0, v62
	v_pk_fma_f32 v[64:65], v[70:71], v[64:65], s[72:73] op_sel_hi:[1,1,0]
	s_nop 0
	v_pk_mul_f32 v[64:65], v[70:71], v[64:65]
	s_nop 0
	v_pk_mul_f32 v[64:65], v[66:67], v[64:65]
	s_nop 0
	v_pk_mul_f32 v[66:67], v[62:63], v[64:65]
	v_pk_fma_f32 v[64:65], v[62:63], v[64:65], v[62:63] neg_lo:[1,0,0] neg_hi:[1,0,0]
	s_nop 0
	v_cndmask_b32_e32 v62, v64, v66, vcc
	v_mul_f32_e32 v66, 0xbfb8aa3b, v57
	v_mul_f32_e32 v64, 0xbfb8aa3b, v56
	v_exp_f32_e32 v66, v66
	v_exp_f32_e32 v64, v64
	v_cmp_gt_f32_e32 vcc, 0, v63
	v_add_f32_e32 v64, 1.0, v64
	s_nop 0
	v_cndmask_b32_e32 v63, v65, v67, vcc
	v_add_f32_e32 v65, 1.0, v66
	v_mul_f32_e32 v66, 0xbfb8aa3b, v58
	v_mul_f32_e32 v67, 0xbfb8aa3b, v59
	v_exp_f32_e32 v66, v66
	v_exp_f32_e32 v67, v67
	v_rcp_f32_e32 v64, v64
	v_rcp_f32_e32 v65, v65
	v_add_f32_e32 v66, 1.0, v66
	v_add_f32_e32 v67, 1.0, v67
	v_rcp_f32_e32 v66, v66
	v_rcp_f32_e32 v67, v67
	v_pk_mul_f32 v[56:57], v[56:57], v[64:65]
	v_and_b32_e32 v65, 0x7fffffff, v53
	v_and_b32_e32 v64, 0x7fffffff, v52
	v_pk_fma_f32 v[64:65], v[64:65], s[28:29], 1.0 op_sel_hi:[1,0,0]
	v_pk_mul_f32 v[58:59], v[58:59], v[66:67]
	v_rcp_f32_e32 v64, v64
	v_rcp_f32_e32 v65, v65
	v_pk_mul_f32 v[58:59], v[62:63], v[58:59]
	v_pk_mul_f32 v[62:63], v[52:53], v[52:53]
	v_pk_mul_f32 v[56:57], v[60:61], v[56:57]
	v_pk_fma_f32 v[60:61], v[64:65], s[30:31], v[150:151] op_sel_hi:[1,0,0]
	v_pk_mul_f32 v[62:63], v[62:63], s[74:75] op_sel_hi:[1,0]
	v_pk_fma_f32 v[60:61], v[64:65], v[60:61], s[36:37] op_sel_hi:[1,1,0]
	v_exp_f32_e32 v62, v62
	v_exp_f32_e32 v63, v63
	v_pk_fma_f32 v[60:61], v[64:65], v[60:61], s[50:51] op_sel_hi:[1,1,0]
	v_and_b32_e32 v67, 0x7fffffff, v55
	v_and_b32_e32 v66, 0x7fffffff, v54
	v_pk_fma_f32 v[60:61], v[64:65], v[60:61], s[72:73] op_sel_hi:[1,1,0]
	v_pk_fma_f32 v[66:67], v[66:67], s[28:29], 1.0 op_sel_hi:[1,0,0]
	v_pk_mul_f32 v[60:61], v[64:65], v[60:61]
	v_rcp_f32_e32 v66, v66
	v_rcp_f32_e32 v67, v67
	v_pk_mul_f32 v[60:61], v[62:63], v[60:61]
	v_cmp_gt_f32_e32 vcc, 0, v52
	v_pk_mul_f32 v[62:63], v[52:53], v[60:61]
	v_pk_fma_f32 v[60:61], v[52:53], v[60:61], v[52:53] neg_lo:[1,0,0] neg_hi:[1,0,0]
	v_pk_mul_f32 v[64:65], v[54:55], v[54:55]
	v_cndmask_b32_e32 v52, v60, v62, vcc
	v_cmp_gt_f32_e32 vcc, 0, v53
	s_nop 1
	v_cndmask_b32_e32 v53, v61, v63, vcc
	v_pk_fma_f32 v[60:61], v[66:67], s[30:31], v[150:151] op_sel_hi:[1,0,0]
	v_pk_mul_f32 v[62:63], v[64:65], s[74:75] op_sel_hi:[1,0]
	v_pk_fma_f32 v[60:61], v[66:67], v[60:61], s[36:37] op_sel_hi:[1,1,0]
	v_exp_f32_e32 v62, v62
	v_exp_f32_e32 v63, v63
	v_pk_fma_f32 v[60:61], v[66:67], v[60:61], s[50:51] op_sel_hi:[1,1,0]
	v_mul_f32_e32 v64, 0xbfb8aa3b, v48
	v_pk_fma_f32 v[60:61], v[66:67], v[60:61], s[72:73] op_sel_hi:[1,1,0]
	v_exp_f32_e32 v64, v64
	v_mul_f32_e32 v65, 0xbfb8aa3b, v49
	v_pk_mul_f32 v[60:61], v[66:67], v[60:61]
	v_exp_f32_e32 v65, v65
	v_pk_mul_f32 v[60:61], v[62:63], v[60:61]
	v_cmp_gt_f32_e32 vcc, 0, v54
	v_pk_mul_f32 v[62:63], v[54:55], v[60:61]
	v_pk_fma_f32 v[60:61], v[54:55], v[60:61], v[54:55] neg_lo:[1,0,0] neg_hi:[1,0,0]
	s_nop 0
	v_cndmask_b32_e32 v54, v60, v62, vcc
	v_add_f32_e32 v60, 1.0, v64
	v_mul_f32_e32 v62, 0xbfb8aa3b, v50
	v_rcp_f32_e32 v64, v60
	v_add_f32_e32 v60, 1.0, v65
	v_exp_f32_e32 v62, v62
	v_mul_f32_e32 v65, 0xbfb8aa3b, v51
	v_exp_f32_e32 v67, v65
	v_rcp_f32_e32 v65, v60
	v_add_f32_e32 v60, 1.0, v62
	v_rcp_f32_e32 v66, v60
	v_add_f32_e32 v60, 1.0, v67
	v_rcp_f32_e32 v67, v60
	v_cmp_gt_f32_e32 vcc, 0, v55
	v_pk_mul_f32 v[48:49], v[48:49], v[64:65]
	v_pk_mul_f32 v[50:51], v[50:51], v[66:67]
	v_cndmask_b32_e32 v55, v61, v63, vcc
	v_pk_mul_f32 v[54:55], v[54:55], v[50:51]
	v_pk_mul_f32 v[50:51], v[52:53], v[48:49]
	v_and_b32_e32 v53, 0x7fffffff, v45
	v_and_b32_e32 v52, 0x7fffffff, v44
	v_pk_fma_f32 v[52:53], v[52:53], s[28:29], 1.0 op_sel_hi:[1,0,0]
	v_cvt_pk_bf16_f32 v48, v56, v57
	v_cvt_pk_bf16_f32 v49, v58, v59
	v_cvt_pk_bf16_f32 v50, v50, v51
	v_cvt_pk_bf16_f32 v51, v54, v55
	v_add_co_u32_e32 v54, vcc, s6, v148
; __device__ __forceinline__ unsigned cvt_pk_bf16(float lo, float hi) { unsigned r; asm volatile("v_cvt_pk_bf16_f32 %0, %1, %2" : "=v"(r) : "v"(lo), "v"(hi)); return r; }
; __device__ __forceinline__ f32x4 gelu4(f32x4 v) { f32x2 a = gelu_pk((f32x2){v[0], v[1]}), b = gelu_pk((f32x2){v[2], v[3]}); return (f32x4){a.x, a.y, b.x, b.y}; }
; __device__ __forceinline__ f32x4 silu4(f32x4 v) { return v * sigm4(v); }
;     __device__ __forceinline__ void operator()(const f32x4 (&acc)[2][2][4][2], const pg8::Unit& u, int wr, int wc, int fr, int fq) const {
;     ...
;                 for (int m = 0; m < 4; ++m) {
;                     bf16_t* rowp = base + (size_t)(row0 + ai * 128 + m * 16) * 1024;
;                     const f32x4 v0 = gelu4(acc[ai][0][m][0]) * silu4(acc[ai][1][m][0]), v1 = gelu4(acc[ai][0][m][1]) * silu4(acc[ai][1][m][1]);
;                     u32x4 w; w.x = cvt_pk_bf16(v0[0], v0[1]); w.y = cvt_pk_bf16(v0[2], v0[3]); w.z = cvt_pk_bf16(v1[0], v1[1]); w.w = cvt_pk_bf16(v1[2], v1[3]);
;                     __builtin_nontemporal_store(w, (u32x4*)rowp);
	v_rcp_f32_e32 v52, v52
	v_rcp_f32_e32 v53, v53
	v_addc_co_u32_e32 v55, vcc, 0, v149, vcc
	global_store_dwordx4 v[54:55], v[48:51], off nt
	v_and_b32_e32 v55, 0x7fffffff, v47
	v_and_b32_e32 v54, 0x7fffffff, v46
	v_pk_mul_f32 v[50:51], v[44:45], v[44:45]
	v_pk_fma_f32 v[48:49], v[52:53], s[30:31], v[150:151] op_sel_hi:[1,0,0]
	v_pk_mul_f32 v[50:51], v[50:51], s[74:75] op_sel_hi:[1,0]
	v_pk_fma_f32 v[48:49], v[52:53], v[48:49], s[36:37] op_sel_hi:[1,1,0]
	v_exp_f32_e32 v50, v50
	v_exp_f32_e32 v51, v51
	v_pk_fma_f32 v[48:49], v[52:53], v[48:49], s[50:51] op_sel_hi:[1,1,0]
	v_pk_fma_f32 v[54:55], v[54:55], s[28:29], 1.0 op_sel_hi:[1,0,0]
	v_pk_fma_f32 v[48:49], v[52:53], v[48:49], s[72:73] op_sel_hi:[1,1,0]
	v_rcp_f32_e32 v54, v54
	v_pk_mul_f32 v[48:49], v[52:53], v[48:49]
	v_rcp_f32_e32 v55, v55
	v_pk_mul_f32 v[48:49], v[50:51], v[48:49]
	v_cmp_gt_f32_e32 vcc, 0, v44
	v_pk_mul_f32 v[50:51], v[44:45], v[48:49]
	v_pk_fma_f32 v[48:49], v[44:45], v[48:49], v[44:45] neg_lo:[1,0,0] neg_hi:[1,0,0]
	v_pk_mul_f32 v[52:53], v[46:47], v[46:47]
	v_cndmask_b32_e32 v44, v48, v50, vcc
	v_cmp_gt_f32_e32 vcc, 0, v45
	s_mov_b32 s6, 0x48000
	s_nop 0
	v_cndmask_b32_e32 v45, v49, v51, vcc
	v_pk_fma_f32 v[48:49], v[54:55], s[30:31], v[150:151] op_sel_hi:[1,0,0]
	v_pk_mul_f32 v[50:51], v[52:53], s[74:75] op_sel_hi:[1,0]
	v_pk_fma_f32 v[48:49], v[54:55], v[48:49], s[36:37] op_sel_hi:[1,1,0]
	v_exp_f32_e32 v50, v50
	v_exp_f32_e32 v51, v51
	v_pk_fma_f32 v[48:49], v[54:55], v[48:49], s[50:51] op_sel_hi:[1,1,0]
	v_cmp_gt_f32_e32 vcc, 0, v46
	v_pk_fma_f32 v[48:49], v[54:55], v[48:49], s[72:73] op_sel_hi:[1,1,0]
	s_nop 0
	v_pk_mul_f32 v[48:49], v[54:55], v[48:49]
	s_nop 0
	v_pk_mul_f32 v[48:49], v[50:51], v[48:49]
	s_nop 0
	v_pk_mul_f32 v[50:51], v[46:47], v[48:49]
	v_pk_fma_f32 v[48:49], v[46:47], v[48:49], v[46:47] neg_lo:[1,0,0] neg_hi:[1,0,0]
	s_nop 0
	v_cndmask_b32_e32 v46, v48, v50, vcc
	v_mul_f32_e32 v50, 0xbfb8aa3b, v41
	v_mul_f32_e32 v48, 0xbfb8aa3b, v40
	v_exp_f32_e32 v50, v50
	v_exp_f32_e32 v48, v48
	v_cmp_gt_f32_e32 vcc, 0, v47
	v_add_f32_e32 v48, 1.0, v48
	s_nop 0
	v_cndmask_b32_e32 v47, v49, v51, vcc
	v_add_f32_e32 v49, 1.0, v50
	v_mul_f32_e32 v50, 0xbfb8aa3b, v42
	v_mul_f32_e32 v51, 0xbfb8aa3b, v43
	v_exp_f32_e32 v50, v50
	v_exp_f32_e32 v51, v51
	v_rcp_f32_e32 v48, v48
	v_rcp_f32_e32 v49, v49
	v_add_f32_e32 v50, 1.0, v50
	v_add_f32_e32 v51, 1.0, v51
	v_rcp_f32_e32 v50, v50
	v_rcp_f32_e32 v51, v51
	v_pk_mul_f32 v[40:41], v[40:41], v[48:49]
	v_and_b32_e32 v49, 0x7fffffff, v37
	v_and_b32_e32 v48, 0x7fffffff, v36
	v_pk_fma_f32 v[48:49], v[48:49], s[28:29], 1.0 op_sel_hi:[1,0,0]
	v_pk_mul_f32 v[42:43], v[42:43], v[50:51]
	v_rcp_f32_e32 v48, v48
	v_rcp_f32_e32 v49, v49
	v_pk_mul_f32 v[42:43], v[46:47], v[42:43]
	v_pk_mul_f32 v[46:47], v[36:37], v[36:37]
	v_pk_mul_f32 v[40:41], v[44:45], v[40:41]
	v_pk_fma_f32 v[44:45], v[48:49], s[30:31], v[150:151] op_sel_hi:[1,0,0]
	v_pk_mul_f32 v[46:47], v[46:47], s[74:75] op_sel_hi:[1,0]
	v_pk_fma_f32 v[44:45], v[48:49], v[44:45], s[36:37] op_sel_hi:[1,1,0]
	v_exp_f32_e32 v46, v46
	v_exp_f32_e32 v47, v47
	v_pk_fma_f32 v[44:45], v[48:49], v[44:45], s[50:51] op_sel_hi:[1,1,0]
	v_and_b32_e32 v51, 0x7fffffff, v39
	v_and_b32_e32 v50, 0x7fffffff, v38
	v_pk_fma_f32 v[44:45], v[48:49], v[44:45], s[72:73] op_sel_hi:[1,1,0]
	v_pk_fma_f32 v[50:51], v[50:51], s[28:29], 1.0 op_sel_hi:[1,0,0]
	v_pk_mul_f32 v[44:45], v[48:49], v[44:45]
	v_rcp_f32_e32 v50, v50
	v_rcp_f32_e32 v51, v51
	v_pk_mul_f32 v[44:45], v[46:47], v[44:45]
	v_cmp_gt_f32_e32 vcc, 0, v36
	v_pk_mul_f32 v[46:47], v[36:37], v[44:45]
	v_pk_fma_f32 v[44:45], v[36:37], v[44:45], v[36:37] neg_lo:[1,0,0] neg_hi:[1,0,0]
	v_pk_mul_f32 v[48:49], v[38:39], v[38:39]
	v_cndmask_b32_e32 v36, v44, v46, vcc
	v_cmp_gt_f32_e32 vcc, 0, v37
	s_nop 1
	v_cndmask_b32_e32 v37, v45, v47, vcc
	v_pk_fma_f32 v[44:45], v[50:51], s[30:31], v[150:151] op_sel_hi:[1,0,0]
	v_pk_mul_f32 v[46:47], v[48:49], s[74:75] op_sel_hi:[1,0]
	v_pk_fma_f32 v[44:45], v[50:51], v[44:45], s[36:37] op_sel_hi:[1,1,0]
	v_exp_f32_e32 v46, v46
	v_exp_f32_e32 v47, v47
	v_pk_fma_f32 v[44:45], v[50:51], v[44:45], s[50:51] op_sel_hi:[1,1,0]
	v_mul_f32_e32 v48, 0xbfb8aa3b, v32
	v_pk_fma_f32 v[44:45], v[50:51], v[44:45], s[72:73] op_sel_hi:[1,1,0]
	v_exp_f32_e32 v48, v48
	v_mul_f32_e32 v49, 0xbfb8aa3b, v33
	v_pk_mul_f32 v[44:45], v[50:51], v[44:45]
	v_exp_f32_e32 v49, v49
	v_pk_mul_f32 v[44:45], v[46:47], v[44:45]
	v_cmp_gt_f32_e32 vcc, 0, v38
	v_pk_mul_f32 v[46:47], v[38:39], v[44:45]
	v_pk_fma_f32 v[44:45], v[38:39], v[44:45], v[38:39] neg_lo:[1,0,0] neg_hi:[1,0,0]
	s_nop 0
	v_cndmask_b32_e32 v38, v44, v46, vcc
	v_add_f32_e32 v44, 1.0, v48
	v_mul_f32_e32 v46, 0xbfb8aa3b, v34
	v_rcp_f32_e32 v48, v44
	v_add_f32_e32 v44, 1.0, v49
	v_exp_f32_e32 v46, v46
	v_mul_f32_e32 v49, 0xbfb8aa3b, v35
	v_exp_f32_e32 v51, v49
	v_rcp_f32_e32 v49, v44
	v_add_f32_e32 v44, 1.0, v46
	v_rcp_f32_e32 v50, v44
	v_add_f32_e32 v44, 1.0, v51
	v_rcp_f32_e32 v51, v44
	v_cmp_gt_f32_e32 vcc, 0, v39
	v_pk_mul_f32 v[32:33], v[32:33], v[48:49]
	v_pk_mul_f32 v[34:35], v[34:35], v[50:51]
	v_cndmask_b32_e32 v39, v45, v47, vcc
	v_pk_mul_f32 v[38:39], v[38:39], v[34:35]
	v_pk_mul_f32 v[34:35], v[36:37], v[32:33]
	v_and_b32_e32 v37, 0x7fffffff, v29
	v_and_b32_e32 v36, 0x7fffffff, v28
	v_pk_fma_f32 v[36:37], v[36:37], s[28:29], 1.0 op_sel_hi:[1,0,0]
	v_cvt_pk_bf16_f32 v32, v40, v41
	v_cvt_pk_bf16_f32 v33, v42, v43
	v_cvt_pk_bf16_f32 v34, v34, v35
	v_cvt_pk_bf16_f32 v35, v38, v39
	v_add_co_u32_e32 v38, vcc, s6, v148
	v_rcp_f32_e32 v36, v36
	v_rcp_f32_e32 v37, v37
	v_addc_co_u32_e32 v39, vcc, 0, v149, vcc
	global_store_dwordx4 v[38:39], v[32:35], off nt
; __device__ __forceinline__ unsigned cvt_pk_bf16(float lo, float hi) { unsigned r; asm volatile("v_cvt_pk_bf16_f32 %0, %1, %2" : "=v"(r) : "v"(lo), "v"(hi)); return r; }
; __device__ __forceinline__ f32x4 gelu4(f32x4 v) { f32x2 a = gelu_pk((f32x2){v[0], v[1]}), b = gelu_pk((f32x2){v[2], v[3]}); return (f32x4){a.x, a.y, b.x, b.y}; }
; __device__ __forceinline__ f32x4 silu4(f32x4 v) { return v * sigm4(v); }
; #define PG8_BAR __builtin_amdgcn_s_barrier()
; template <class Epi>
; __device__ __forceinline__ void gemm_phase(LAS unsigned char* lds, const Gemm g, const StaticOrder& S, const Epi& E) {
;     ...
;         if (wr == 1) PG8_BAR;
;     __device__ __forceinline__ void operator()(const f32x4 (&acc)[2][2][4][2], const pg8::Unit& u, int wr, int wc, int fr, int fq) const {
;     ...
;                 for (int m = 0; m < 4; ++m) {
;                     bf16_t* rowp = base + (size_t)(row0 + ai * 128 + m * 16) * 1024;
;                     const f32x4 v0 = gelu4(acc[ai][0][m][0]) * silu4(acc[ai][1][m][0]), v1 = gelu4(acc[ai][0][m][1]) * silu4(acc[ai][1][m][1]);
;                     u32x4 w; w.x = cvt_pk_bf16(v0[0], v0[1]); w.y = cvt_pk_bf16(v0[2], v0[3]); w.z = cvt_pk_bf16(v1[0], v1[1]); w.w = cvt_pk_bf16(v1[2], v1[3]);
;                     __builtin_nontemporal_store(w, (u32x4*)rowp);
	v_and_b32_e32 v39, 0x7fffffff, v31
	v_and_b32_e32 v38, 0x7fffffff, v30
	v_pk_mul_f32 v[34:35], v[28:29], v[28:29]
	v_pk_fma_f32 v[32:33], v[36:37], s[30:31], v[150:151] op_sel_hi:[1,0,0]
	v_pk_mul_f32 v[34:35], v[34:35], s[74:75] op_sel_hi:[1,0]
	v_pk_fma_f32 v[32:33], v[36:37], v[32:33], s[36:37] op_sel_hi:[1,1,0]
	v_exp_f32_e32 v34, v34
	v_exp_f32_e32 v35, v35
	v_pk_fma_f32 v[32:33], v[36:37], v[32:33], s[50:51] op_sel_hi:[1,1,0]
	v_pk_fma_f32 v[38:39], v[38:39], s[28:29], 1.0 op_sel_hi:[1,0,0]
	v_pk_fma_f32 v[32:33], v[36:37], v[32:33], s[72:73] op_sel_hi:[1,1,0]
	v_rcp_f32_e32 v38, v38
	v_pk_mul_f32 v[32:33], v[36:37], v[32:33]
	v_rcp_f32_e32 v39, v39
	v_pk_mul_f32 v[32:33], v[34:35], v[32:33]
	v_cmp_gt_f32_e32 vcc, 0, v28
	v_pk_mul_f32 v[34:35], v[28:29], v[32:33]
	v_pk_fma_f32 v[32:33], v[28:29], v[32:33], v[28:29] neg_lo:[1,0,0] neg_hi:[1,0,0]
	v_pk_mul_f32 v[36:37], v[30:31], v[30:31]
	v_cndmask_b32_e32 v28, v32, v34, vcc
	v_cmp_gt_f32_e32 vcc, 0, v29
	s_mov_b32 s6, 0x50000
	s_nop 0
	v_cndmask_b32_e32 v29, v33, v35, vcc
	v_pk_fma_f32 v[32:33], v[38:39], s[30:31], v[150:151] op_sel_hi:[1,0,0]
	v_pk_mul_f32 v[34:35], v[36:37], s[74:75] op_sel_hi:[1,0]
	v_pk_fma_f32 v[32:33], v[38:39], v[32:33], s[36:37] op_sel_hi:[1,1,0]
	v_exp_f32_e32 v34, v34
	v_exp_f32_e32 v35, v35
	v_pk_fma_f32 v[32:33], v[38:39], v[32:33], s[50:51] op_sel_hi:[1,1,0]
	v_cmp_gt_f32_e32 vcc, 0, v30
	v_pk_fma_f32 v[32:33], v[38:39], v[32:33], s[72:73] op_sel_hi:[1,1,0]
	s_nop 0
	v_pk_mul_f32 v[32:33], v[38:39], v[32:33]
	s_nop 0
	v_pk_mul_f32 v[32:33], v[34:35], v[32:33]
	s_nop 0
	v_pk_mul_f32 v[34:35], v[30:31], v[32:33]
	v_pk_fma_f32 v[32:33], v[30:31], v[32:33], v[30:31] neg_lo:[1,0,0] neg_hi:[1,0,0]
	s_nop 0
	v_cndmask_b32_e32 v30, v32, v34, vcc
	v_mul_f32_e32 v34, 0xbfb8aa3b, v25
	v_mul_f32_e32 v32, 0xbfb8aa3b, v24
	v_exp_f32_e32 v34, v34
	v_exp_f32_e32 v32, v32
	v_cmp_gt_f32_e32 vcc, 0, v31
	v_add_f32_e32 v32, 1.0, v32
	s_nop 0
	v_cndmask_b32_e32 v31, v33, v35, vcc
	v_add_f32_e32 v33, 1.0, v34
	v_mul_f32_e32 v34, 0xbfb8aa3b, v26
	v_mul_f32_e32 v35, 0xbfb8aa3b, v27
	v_exp_f32_e32 v34, v34
	v_exp_f32_e32 v35, v35
	v_rcp_f32_e32 v32, v32
	v_rcp_f32_e32 v33, v33
	v_add_f32_e32 v34, 1.0, v34
	v_add_f32_e32 v35, 1.0, v35
	v_rcp_f32_e32 v34, v34
	v_rcp_f32_e32 v35, v35
	v_pk_mul_f32 v[24:25], v[24:25], v[32:33]
	v_and_b32_e32 v33, 0x7fffffff, v21
	v_and_b32_e32 v32, 0x7fffffff, v20
	v_pk_fma_f32 v[32:33], v[32:33], s[28:29], 1.0 op_sel_hi:[1,0,0]
	v_pk_mul_f32 v[26:27], v[26:27], v[34:35]
	v_rcp_f32_e32 v32, v32
	v_rcp_f32_e32 v33, v33
	v_pk_mul_f32 v[26:27], v[30:31], v[26:27]
	v_pk_mul_f32 v[30:31], v[20:21], v[20:21]
	v_pk_mul_f32 v[24:25], v[28:29], v[24:25]
	v_pk_fma_f32 v[28:29], v[32:33], s[30:31], v[150:151] op_sel_hi:[1,0,0]
	v_pk_mul_f32 v[30:31], v[30:31], s[74:75] op_sel_hi:[1,0]
	v_pk_fma_f32 v[28:29], v[32:33], v[28:29], s[36:37] op_sel_hi:[1,1,0]
	v_exp_f32_e32 v30, v30
	v_exp_f32_e32 v31, v31
	v_pk_fma_f32 v[28:29], v[32:33], v[28:29], s[50:51] op_sel_hi:[1,1,0]
	v_and_b32_e32 v35, 0x7fffffff, v23
	v_and_b32_e32 v34, 0x7fffffff, v22
	v_pk_fma_f32 v[28:29], v[32:33], v[28:29], s[72:73] op_sel_hi:[1,1,0]
	v_pk_fma_f32 v[34:35], v[34:35], s[28:29], 1.0 op_sel_hi:[1,0,0]
	v_pk_mul_f32 v[28:29], v[32:33], v[28:29]
	v_rcp_f32_e32 v34, v34
	v_rcp_f32_e32 v35, v35
	v_pk_mul_f32 v[28:29], v[30:31], v[28:29]
	v_cmp_gt_f32_e32 vcc, 0, v20
	v_pk_mul_f32 v[30:31], v[20:21], v[28:29]
	v_pk_fma_f32 v[28:29], v[20:21], v[28:29], v[20:21] neg_lo:[1,0,0] neg_hi:[1,0,0]
	v_pk_mul_f32 v[32:33], v[22:23], v[22:23]
	v_cndmask_b32_e32 v20, v28, v30, vcc
	v_cmp_gt_f32_e32 vcc, 0, v21
	s_nop 1
	v_cndmask_b32_e32 v21, v29, v31, vcc
	v_pk_fma_f32 v[28:29], v[34:35], s[30:31], v[150:151] op_sel_hi:[1,0,0]
	v_pk_mul_f32 v[30:31], v[32:33], s[74:75] op_sel_hi:[1,0]
	v_pk_fma_f32 v[28:29], v[34:35], v[28:29], s[36:37] op_sel_hi:[1,1,0]
	v_exp_f32_e32 v30, v30
	v_exp_f32_e32 v31, v31
	v_pk_fma_f32 v[28:29], v[34:35], v[28:29], s[50:51] op_sel_hi:[1,1,0]
	v_mul_f32_e32 v32, 0xbfb8aa3b, v16
	v_pk_fma_f32 v[28:29], v[34:35], v[28:29], s[72:73] op_sel_hi:[1,1,0]
	v_exp_f32_e32 v32, v32
	v_mul_f32_e32 v33, 0xbfb8aa3b, v17
	v_pk_mul_f32 v[28:29], v[34:35], v[28:29]
	v_exp_f32_e32 v33, v33
	v_pk_mul_f32 v[28:29], v[30:31], v[28:29]
	v_cmp_gt_f32_e32 vcc, 0, v22
	v_pk_mul_f32 v[30:31], v[22:23], v[28:29]
	v_pk_fma_f32 v[28:29], v[22:23], v[28:29], v[22:23] neg_lo:[1,0,0] neg_hi:[1,0,0]
	s_nop 0
	v_cndmask_b32_e32 v22, v28, v30, vcc
	v_add_f32_e32 v28, 1.0, v32
	v_mul_f32_e32 v30, 0xbfb8aa3b, v18
	v_rcp_f32_e32 v32, v28
	v_add_f32_e32 v28, 1.0, v33
	v_exp_f32_e32 v30, v30
	v_mul_f32_e32 v33, 0xbfb8aa3b, v19
	v_exp_f32_e32 v35, v33
	v_rcp_f32_e32 v33, v28
	v_add_f32_e32 v28, 1.0, v30
	v_rcp_f32_e32 v34, v28
	v_add_f32_e32 v28, 1.0, v35
	v_rcp_f32_e32 v35, v28
	v_cmp_gt_f32_e32 vcc, 0, v23
	v_pk_mul_f32 v[16:17], v[16:17], v[32:33]
	v_pk_mul_f32 v[18:19], v[18:19], v[34:35]
	v_cndmask_b32_e32 v23, v29, v31, vcc
	v_pk_mul_f32 v[22:23], v[22:23], v[18:19]
	v_pk_mul_f32 v[18:19], v[20:21], v[16:17]
	v_and_b32_e32 v21, 0x7fffffff, v13
	v_and_b32_e32 v20, 0x7fffffff, v12
	v_pk_fma_f32 v[20:21], v[20:21], s[28:29], 1.0 op_sel_hi:[1,0,0]
	v_cvt_pk_bf16_f32 v16, v24, v25
	v_cvt_pk_bf16_f32 v17, v26, v27
	v_cvt_pk_bf16_f32 v18, v18, v19
	v_cvt_pk_bf16_f32 v19, v22, v23
	v_add_co_u32_e32 v22, vcc, s6, v148
	v_rcp_f32_e32 v20, v20
	v_rcp_f32_e32 v21, v21
	v_addc_co_u32_e32 v23, vcc, 0, v149, vcc
	global_store_dwordx4 v[22:23], v[16:19], off nt
	s_and_b64 s[98:99], s[4:5], s[14:15]
	s_cbranch_scc0 .Lepi_rb_b
	s_barrier
; __device__ __forceinline__ unsigned cvt_pk_bf16(float lo, float hi) { unsigned r; asm volatile("v_cvt_pk_bf16_f32 %0, %1, %2" : "=v"(r) : "v"(lo), "v"(hi)); return r; }
; __device__ __forceinline__ f32x4 gelu4(f32x4 v) { f32x2 a = gelu_pk((f32x2){v[0], v[1]}), b = gelu_pk((f32x2){v[2], v[3]}); return (f32x4){a.x, a.y, b.x, b.y}; }
; __device__ __forceinline__ f32x4 silu4(f32x4 v) { return v * sigm4(v); }
; #define PG8_BAR __builtin_amdgcn_s_barrier()
; template <class Epi>
; __device__ __forceinline__ void gemm_phase(LAS unsigned char* lds, const Gemm g, const StaticOrder& S, const Epi& E) {
;     ...
;         if (wr == 1) PG8_BAR;
;     __device__ __forceinline__ void operator()(const f32x4 (&acc)[2][2][4][2], const pg8::Unit& u, int wr, int wc, int fr, int fq) const {
;     ...
;                 for (int m = 0; m < 4; ++m) {
;                     bf16_t* rowp = base + (size_t)(row0 + ai * 128 + m * 16) * 1024;
;                     const f32x4 v0 = gelu4(acc[ai][0][m][0]) * silu4(acc[ai][1][m][0]), v1 = gelu4(acc[ai][0][m][1]) * silu4(acc[ai][1][m][1]);
;                     u32x4 w; w.x = cvt_pk_bf16(v0[0], v0[1]); w.y = cvt_pk_bf16(v0[2], v0[3]); w.z = cvt_pk_bf16(v1[0], v1[1]); w.w = cvt_pk_bf16(v1[2], v1[3]);
;                     __builtin_nontemporal_store(w, (u32x4*)rowp);
.Lepi_rb_b:
	v_and_b32_e32 v23, 0x7fffffff, v15
	v_and_b32_e32 v22, 0x7fffffff, v14
	v_pk_mul_f32 v[18:19], v[12:13], v[12:13]
	v_pk_fma_f32 v[16:17], v[20:21], s[30:31], v[150:151] op_sel_hi:[1,0,0]
	v_pk_mul_f32 v[18:19], v[18:19], s[74:75] op_sel_hi:[1,0]
	v_pk_fma_f32 v[16:17], v[20:21], v[16:17], s[36:37] op_sel_hi:[1,1,0]
	v_exp_f32_e32 v18, v18
	v_exp_f32_e32 v19, v19
	v_pk_fma_f32 v[16:17], v[20:21], v[16:17], s[50:51] op_sel_hi:[1,1,0]
	v_pk_fma_f32 v[22:23], v[22:23], s[28:29], 1.0 op_sel_hi:[1,0,0]
	v_pk_fma_f32 v[16:17], v[20:21], v[16:17], s[72:73] op_sel_hi:[1,1,0]
	v_rcp_f32_e32 v22, v22
	v_pk_mul_f32 v[16:17], v[20:21], v[16:17]
	v_rcp_f32_e32 v23, v23
	v_pk_mul_f32 v[16:17], v[18:19], v[16:17]
	v_cmp_gt_f32_e32 vcc, 0, v12
	v_pk_mul_f32 v[18:19], v[12:13], v[16:17]
	v_pk_fma_f32 v[16:17], v[12:13], v[16:17], v[12:13] neg_lo:[1,0,0] neg_hi:[1,0,0]
	v_pk_mul_f32 v[20:21], v[14:15], v[14:15]
	v_cndmask_b32_e32 v12, v16, v18, vcc
	v_cmp_gt_f32_e32 vcc, 0, v13
	s_nop 1
	v_cndmask_b32_e32 v13, v17, v19, vcc
	v_pk_fma_f32 v[16:17], v[22:23], s[30:31], v[150:151] op_sel_hi:[1,0,0]
	v_pk_mul_f32 v[18:19], v[20:21], s[74:75] op_sel_hi:[1,0]
	v_pk_fma_f32 v[16:17], v[22:23], v[16:17], s[36:37] op_sel_hi:[1,1,0]
	v_exp_f32_e32 v18, v18
	v_exp_f32_e32 v19, v19
	v_pk_fma_f32 v[16:17], v[22:23], v[16:17], s[50:51] op_sel_hi:[1,1,0]
	v_cmp_gt_f32_e32 vcc, 0, v14
	v_pk_fma_f32 v[16:17], v[22:23], v[16:17], s[72:73] op_sel_hi:[1,1,0]
	s_nop 0
	v_pk_mul_f32 v[16:17], v[22:23], v[16:17]
	s_nop 0
	v_pk_mul_f32 v[16:17], v[18:19], v[16:17]
	s_nop 0
	v_pk_mul_f32 v[18:19], v[14:15], v[16:17]
	v_pk_fma_f32 v[16:17], v[14:15], v[16:17], v[14:15] neg_lo:[1,0,0] neg_hi:[1,0,0]
	s_nop 0
	v_cndmask_b32_e32 v14, v16, v18, vcc
	v_mul_f32_e32 v18, 0xbfb8aa3b, v9
	v_mul_f32_e32 v16, 0xbfb8aa3b, v8
	v_exp_f32_e32 v18, v18
	v_exp_f32_e32 v16, v16
	v_cmp_gt_f32_e32 vcc, 0, v15
	v_add_f32_e32 v16, 1.0, v16
	s_nop 0
	v_cndmask_b32_e32 v15, v17, v19, vcc
	v_add_f32_e32 v17, 1.0, v18
	v_mul_f32_e32 v18, 0xbfb8aa3b, v10
	v_mul_f32_e32 v19, 0xbfb8aa3b, v11
	v_exp_f32_e32 v18, v18
	v_exp_f32_e32 v19, v19
	v_rcp_f32_e32 v16, v16
	v_rcp_f32_e32 v17, v17
	v_add_f32_e32 v18, 1.0, v18
	v_add_f32_e32 v19, 1.0, v19
	v_rcp_f32_e32 v18, v18
	v_rcp_f32_e32 v19, v19
	v_pk_mul_f32 v[8:9], v[8:9], v[16:17]
	v_and_b32_e32 v17, 0x7fffffff, v5
	v_and_b32_e32 v16, 0x7fffffff, v4
	v_pk_fma_f32 v[16:17], v[16:17], s[28:29], 1.0 op_sel_hi:[1,0,0]
	v_pk_mul_f32 v[10:11], v[10:11], v[18:19]
	v_rcp_f32_e32 v16, v16
	v_rcp_f32_e32 v17, v17
	v_pk_mul_f32 v[10:11], v[14:15], v[10:11]
	v_pk_mul_f32 v[14:15], v[4:5], v[4:5]
	v_pk_mul_f32 v[8:9], v[12:13], v[8:9]
	v_pk_fma_f32 v[12:13], v[16:17], s[30:31], v[150:151] op_sel_hi:[1,0,0]
	v_pk_mul_f32 v[14:15], v[14:15], s[74:75] op_sel_hi:[1,0]
	v_pk_fma_f32 v[12:13], v[16:17], v[12:13], s[36:37] op_sel_hi:[1,1,0]
	v_exp_f32_e32 v14, v14
	v_exp_f32_e32 v15, v15
	v_pk_fma_f32 v[12:13], v[16:17], v[12:13], s[50:51] op_sel_hi:[1,1,0]
	v_and_b32_e32 v19, 0x7fffffff, v7
	v_and_b32_e32 v18, 0x7fffffff, v6
	v_pk_fma_f32 v[12:13], v[16:17], v[12:13], s[72:73] op_sel_hi:[1,1,0]
	v_pk_fma_f32 v[18:19], v[18:19], s[28:29], 1.0 op_sel_hi:[1,0,0]
	v_pk_mul_f32 v[12:13], v[16:17], v[12:13]
	v_rcp_f32_e32 v18, v18
	v_rcp_f32_e32 v19, v19
	v_pk_mul_f32 v[12:13], v[14:15], v[12:13]
	v_cmp_gt_f32_e32 vcc, 0, v4
	v_pk_mul_f32 v[14:15], v[4:5], v[12:13]
	v_pk_fma_f32 v[12:13], v[4:5], v[12:13], v[4:5] neg_lo:[1,0,0] neg_hi:[1,0,0]
	v_pk_mul_f32 v[16:17], v[6:7], v[6:7]
	v_cndmask_b32_e32 v4, v12, v14, vcc
	v_cmp_gt_f32_e32 vcc, 0, v5
	s_nop 1
	v_cndmask_b32_e32 v5, v13, v15, vcc
	v_pk_fma_f32 v[12:13], v[18:19], s[30:31], v[150:151] op_sel_hi:[1,0,0]
	v_pk_mul_f32 v[14:15], v[16:17], s[74:75] op_sel_hi:[1,0]
	v_pk_fma_f32 v[12:13], v[18:19], v[12:13], s[36:37] op_sel_hi:[1,1,0]
	v_exp_f32_e32 v14, v14
	v_exp_f32_e32 v15, v15
	v_pk_fma_f32 v[12:13], v[18:19], v[12:13], s[50:51] op_sel_hi:[1,1,0]
	v_mul_f32_e32 v16, 0xbfb8aa3b, v0
	v_pk_fma_f32 v[12:13], v[18:19], v[12:13], s[72:73] op_sel_hi:[1,1,0]
	v_exp_f32_e32 v16, v16
	v_mul_f32_e32 v17, 0xbfb8aa3b, v1
	v_pk_mul_f32 v[12:13], v[18:19], v[12:13]
	v_exp_f32_e32 v17, v17
	v_pk_mul_f32 v[12:13], v[14:15], v[12:13]
	v_cmp_gt_f32_e32 vcc, 0, v6
	v_pk_mul_f32 v[14:15], v[6:7], v[12:13]
	v_pk_fma_f32 v[12:13], v[6:7], v[12:13], v[6:7] neg_lo:[1,0,0] neg_hi:[1,0,0]
	s_nop 0
	v_cndmask_b32_e32 v6, v12, v14, vcc
	v_add_f32_e32 v12, 1.0, v16
	v_mul_f32_e32 v14, 0xbfb8aa3b, v2
	v_rcp_f32_e32 v16, v12
	v_add_f32_e32 v12, 1.0, v17
	v_exp_f32_e32 v14, v14
	v_mul_f32_e32 v17, 0xbfb8aa3b, v3
	v_exp_f32_e32 v19, v17
	v_rcp_f32_e32 v17, v12
	v_add_f32_e32 v12, 1.0, v14
	v_rcp_f32_e32 v18, v12
	v_add_f32_e32 v12, 1.0, v19
	v_rcp_f32_e32 v19, v12
	v_cmp_gt_f32_e32 vcc, 0, v7
	v_pk_mul_f32 v[0:1], v[0:1], v[16:17]
	v_pk_mul_f32 v[2:3], v[2:3], v[18:19]
	v_cndmask_b32_e32 v7, v13, v15, vcc
	v_pk_mul_f32 v[6:7], v[6:7], v[2:3]
	v_pk_mul_f32 v[2:3], v[4:5], v[0:1]
	v_add_co_u32_e32 v4, vcc, 0x58000, v148
	v_cvt_pk_bf16_f32 v0, v8, v9
	v_cvt_pk_bf16_f32 v1, v10, v11
	v_cvt_pk_bf16_f32 v2, v2, v3
	v_cvt_pk_bf16_f32 v3, v6, v7
	s_nop 1
	v_addc_co_u32_e32 v5, vcc, 0, v149, vcc
	global_store_dwordx4 v[4:5], v[0:3], off nt
	s_andn2_b64 vcc, exec, s[4:5]
	s_mov_b64 s[4:5], -1
	s_cbranch_vccnz .LBB0_152
.LBB0_412:
	s_andn2_b64 vcc, exec, s[14:15]
	s_cbranch_vccnz .LBB0_151
	s_branch .LBB0_151
